# diff job prologue: bias-table entry load no longer waited for before the Q/K/V loads are issued (scale + LDS write moved behind them)
# baseline (speedup 1.0000x reference)
; DI int swap23(int k) { return (k & ~12) | ((k & 4) << 1) | ((k & 8) >> 1); }
; DI void build_lut(const Params& p, int bias_head, unsigned char* smem, int tid) {
;   float* lut = (float*)(smem + LUT_OFF);
;   const int d = tid;
;   if (d <= 128) {
;     int bucket;
;     if (d < 16) bucket = d;
;     else {
;       float nf = (float)d;
;       int large = 16 + (int)(logf(nf / 16.f) / 2.0794415416798357f * 16.f);
;       bucket = large < 31 ? large : 31;
;     }
;     lut[d] = p.rel_bias[bucket * 8 + bias_head] * LOG2E;
;   }
; }
; DI void diff_job8(const Params& p, int layer, int b, int head, int qb, unsigned char* smem) {
;   int tid_ = threadIdx.x; asm volatile("" : "+v"(tid_));
;   const int tid = tid_, lane = tid & 63, wave = tid >> 6, h = lane >> 5, lq = lane & 31;
;   const int map = wave >> 2, qg = wave & 3;
;   const int t0 = qb * 128, tw0 = t0 + 32 * qg, tq = tw0 + lq;
;   const float* lut = (const float*)(smem + LUT_OFF);
;   build_lut(p, 4 + head, smem, tid);
;   bf16x8 qf[4];
;   {
;     const u16* qr = p.qdf + (size_t)(b * TP + tq) * 512 + head * 128 + 64 * map + 8 * h;
; #pragma unroll
;     for (int s = 0; s < 4; ++s) qf[s] = *(const bf16x8*)(qr + 16 * s);
;   }
;   f32x16 O[4];
; #pragma unroll
;   for (int i = 0; i < 4; ++i) O[i] = zero16();
;   float m = -1e30f, l = 0.f;
;   const u16* K1 = p.kdf + (size_t)b * TP * 512 + head * 128;
;   const u16* VT = p.vtdf + (size_t)(b * 512 + head * 128) * TP;
;   const int ntile = 2 * (qb + 1);
;   const int krow = tid >> 3, kc = tid & 7, krs = swap23(krow);
;   u32x4 rk1, rk2, rv[2];
;   auto gl = [&](int k0) {
;     const u16* s = K1 + (size_t)(k0 + krow) * 512 + kc * 8;
;     rk1 = *(const u32x4*)s; rk2 = *(const u32x4*)(s + 64);
; #pragma unroll
;     for (int i = 0; i < 2; ++i) rv[i] = *(const u32x4*)(VT + (size_t)(krow + 64 * i) * TP + k0 + kc * 8);
;   };
;   auto sl = [&](unsigned char* d) {
;     *(u32x4*)(d + krs * 144 + kc * 16) = rk1;
;     *(u32x4*)(d + 9216 + krs * 144 + kc * 16) = rk2;
; #pragma unroll
;     for (int i = 0; i < 2; ++i) *(u32x4*)(d + 18432 + (krow + 64 * i) * 144 + kc * 16) = rv[i];
;   };
;   gl(0); sl(smem);
;   if (ntile > 1) gl(64);
;   __syncthreads();
;   const float cbias = lut[128];
.LBB0_917:
	s_or_b64 exec, exec, s[4:5]
	s_load_dwordx16 s[56:71], s[0:1], 0x0
	v_lshlrev_b32_e32 v0, 3, v0
	v_ashrrev_i32_e32 v3, 31, v0
	v_or_b32_e32 v2, s6, v0
	s_waitcnt lgkmcnt(0)
	v_lshl_add_u64 v[2:3], v[2:3], 2, s[60:61]
	global_load_dword v255, v[2:3], off offset:16
	v_lshl_add_u32 v254, v150, 2, v213
.LBB0_918:
	s_or_b64 exec, exec, s[2:3]
	s_ashr_i32 s2, s10, 31
	s_lshr_b32 s2, s2, 27
	s_add_i32 s2, s10, s2
	s_ashr_i32 s2, s2, 5
	v_lshrrev_b32_e32 v0, 1, v150
	s_load_dwordx16 s[56:71], s[0:1], 0x108
	s_sub_i32 s7, 32, s2
	v_and_b32_e32 v149, 0x60, v0
	s_bfe_u32 s4, s10, 0x30002
	v_and_b32_e32 v148, 31, v150
	v_lshl_or_b32 v152, s7, 7, v149
	v_or_b32_e32 v153, v152, v148
	s_mul_i32 s2, s4, 0x1080
	v_add_u32_e32 v0, s2, v153
	s_lshl_b32 s31, s6, 7
	s_lshl_b32 s10, s6, 8
	s_mul_i32 s2, s4, 0x420000
	v_ashrrev_i32_e32 v131, 8, v150
	v_lshlrev_b64 v[2:3], 10, v[0:1]
	s_waitcnt lgkmcnt(0)
	s_add_u32 s2, s58, s2
	v_lshl_add_u64 v[2:3], s[56:57], 0, v[2:3]
	v_lshlrev_b32_e32 v4, 6, v131
	s_addc_u32 s3, s59, 0
	v_bfe_u32 v6, v150, 5, 1
	v_lshl_add_u64 v[2:3], v[2:3], 0, s[10:11]
	v_ashrrev_i32_e32 v5, 31, v4
	s_add_u32 s2, s2, s10
	v_lshlrev_b64 v[132:133], 9, v[0:1]
	v_lshl_add_u64 v[2:3], v[4:5], 1, v[2:3]
	v_lshlrev_b32_e32 v0, 4, v6
	s_addc_u32 s3, s3, 0
	s_lshl_b32 s4, s4, 9
	v_lshl_add_u64 v[2:3], v[2:3], 0, v[0:1]
	s_or_b32 s4, s4, s31
	v_ashrrev_i32_e32 v134, 3, v150
	global_load_dwordx4 v[98:101], v[2:3], off
	global_load_dwordx4 v[102:105], v[2:3], off offset:32
	global_load_dwordx4 v[106:109], v[2:3], off offset:64
	global_load_dwordx4 v[110:113], v[2:3], off offset:96
	s_mulk_i32 s4, 0x2100
	v_lshlrev_b32_e32 v3, 1, v134
	v_lshrrev_b32_e32 v4, 1, v134
	s_add_u32 s4, s64, s4
	v_and_b32_e32 v2, 0xffffff3, v134
	v_and_b32_e32 v3, 8, v3
	v_and_b32_e32 v4, 4, v4
	v_ashrrev_i32_e32 v135, 31, v134
	s_addc_u32 s5, s65, 0
	v_or3_b32 v20, v3, v2, v4
	v_lshlrev_b64 v[2:3], 10, v[134:135]
	v_lshlrev_b32_e32 v4, 4, v150
	v_lshl_add_u64 v[2:3], s[2:3], 0, v[2:3]
	v_and_b32_e32 v136, 0x70, v4
	v_mov_b32_e32 v137, v1
	v_mov_b64_e32 v[14:15], s[4:5]
	s_movk_i32 s6, 0x2100
	v_lshlrev_b32_e32 v130, 3, v6
	v_lshl_add_u64 v[6:7], v[2:3], 0, v[136:137]
	v_mad_i64_i32 v[10:11], s[4:5], v134, s6, v[14:15]
	v_add_u32_e32 v18, 64, v134
	global_load_dwordx4 v[2:5], v[6:7], off
	s_nop 0
	global_load_dwordx4 v[6:9], v[6:7], off offset:128
	v_lshl_add_u64 v[138:139], v[10:11], 0, v[136:137]
	v_mad_i64_i32 v[14:15], s[4:5], v18, s6, v[14:15]
	global_load_dwordx4 v[10:13], v[138:139], off
	v_lshl_add_u64 v[140:141], v[14:15], 0, v[136:137]
	global_load_dwordx4 v[14:17], v[140:141], off
	v_mul_lo_u32 v135, v20, s78
	v_add_u32_e32 v20, v135, v136
	v_mul_lo_u32 v154, v134, s78
	v_ashrrev_i32_e32 v19, 31, v18
	v_mov_b32_e32 v50, v1
	v_mov_b32_e32 v51, v1
	s_lshl_b32 s10, s7, 1
	v_mov_b32_e32 v52, v1
	v_mov_b32_e32 v53, v1
	v_mov_b32_e32 v54, v1
	v_mov_b32_e32 v55, v1
	v_mov_b32_e32 v56, v1
	v_mov_b32_e32 v57, v1
	v_mov_b32_e32 v58, v1
	v_mov_b32_e32 v59, v1
	v_mov_b32_e32 v60, v1
	v_mov_b32_e32 v61, v1
	v_mov_b32_e32 v62, v1
	v_mov_b32_e32 v63, v1
	s_waitcnt vmcnt(19)
	v_mov_b32_e32 v64, v1
	v_mov_b32_e32 v65, v1
	s_waitcnt vmcnt(8)
	v_cmp_gt_i32_e32 vcc, 0x81, v150
	s_and_saveexec_b64 s[8:9], vcc
	v_mul_f32_e32 v255, 0x3fb8aa3b, v255
	ds_write_b32 v254, v255
	s_or_b64 exec, exec, s[8:9]
	v_mov_b64_e32 v[34:35], v[50:51]
	v_and_b32_e32 v151, 63, v150
	s_add_i32 s42, s10, 2
	v_lshl_add_u64 v[142:143], s[2:3], 0, v[136:137]
	v_subrev_u32_e32 v156, 63, v152
	v_add_u32_e32 v157, 0xffffff90, v152
	v_or_b32_e32 v158, 31, v152
	v_mul_u32_u24_e32 v159, 0x90, v148
	v_mov_b32_e32 v161, 0xf149f2ca
	v_mov_b32_e32 v160, 0
	v_mov_b64_e32 v[36:37], v[52:53]
	v_mov_b64_e32 v[38:39], v[54:55]
	s_waitcnt vmcnt(3)
	ds_write_b128 v20, v[2:5]
	s_waitcnt vmcnt(2)
	ds_write_b128 v20, v[6:9] offset:9216
	v_add_u32_e32 v2, v154, v136
	s_waitcnt vmcnt(1)
	ds_write_b128 v2, v[10:13] offset:18432
	s_waitcnt vmcnt(0)
	ds_write_b128 v2, v[14:17] offset:27648
	v_lshlrev_b64 v[2:3], 10, v[18:19]
	v_lshl_add_u64 v[2:3], s[2:3], 0, v[2:3]
	v_lshl_add_u64 v[2:3], v[2:3], 0, v[136:137]
	global_load_dwordx4 v[114:117], v[2:3], off
	global_load_dwordx4 v[118:121], v[2:3], off offset:128
	global_load_dwordx4 v[122:125], v[138:139], off offset:128
	global_load_dwordx4 v[126:129], v[140:141], off offset:128
	v_add_u32_e32 v2, -4, v213
	v_mov_b32_e32 v3, 0xff800000
	ds_write_b32 v2, v3
	s_waitcnt lgkmcnt(0)
	s_barrier
	ds_read_b32 v155, v204
	v_mov_b64_e32 v[2:3], v[50:51]
	v_mov_b64_e32 v[18:19], v[50:51]
	v_mul_i32_i24_e32 v137, 0x2400, v131
	s_mov_b32 s2, 0
	v_mov_b64_e32 v[4:5], v[52:53]
	v_mov_b64_e32 v[6:7], v[54:55]
	v_mov_b64_e32 v[8:9], v[56:57]
	v_mov_b64_e32 v[10:11], v[58:59]
	v_mov_b64_e32 v[12:13], v[60:61]
	v_mov_b64_e32 v[14:15], v[62:63]
	v_mov_b64_e32 v[16:17], v[64:65]
	v_mov_b64_e32 v[20:21], v[52:53]
	v_mov_b64_e32 v[22:23], v[54:55]
	v_mov_b64_e32 v[24:25], v[56:57]
	v_mov_b64_e32 v[26:27], v[58:59]
	v_mov_b64_e32 v[28:29], v[60:61]
	v_mov_b64_e32 v[30:31], v[62:63]
	v_mov_b64_e32 v[32:33], v[64:65]
	v_mov_b64_e32 v[40:41], v[56:57]
	v_mov_b64_e32 v[42:43], v[58:59]
	v_mov_b64_e32 v[44:45], v[60:61]
	v_mov_b64_e32 v[46:47], v[62:63]
	v_mov_b64_e32 v[48:49], v[64:65]
